# v54 with s_sleep removed from the two grid-barrier release poll loops
# speedup vs baseline: 1.0027x; 1.0021x over previous
; __device__ __forceinline__ unsigned xb_ld(unsigned* p)              { return __hip_atomic_load(p, __ATOMIC_RELAXED, __HIP_MEMORY_SCOPE_AGENT); }
; __device__ __forceinline__ unsigned xb_add(unsigned* p, unsigned v) { return __hip_atomic_fetch_add(p, v, __ATOMIC_RELAXED, __HIP_MEMORY_SCOPE_AGENT); }
; #define XB_SPIN(cond, bar) do { unsigned _sp = 0; while (cond) { __builtin_amdgcn_s_sleep(1); \
;     if ((++_sp & 255u) == 0u) { if (xb_ld(&(bar)[XB_TMO])) break; if (_sp > XB_SPIN_CAP) { atomicAdd(&(bar)[XB_TMO], 1u); break; } } } } while (0)
; __device__ __forceinline__ void xcd_barrier(const XcdBarrier& b) {
;     ...
;             else XB_SPIN(xb_ld(&bar[XB_TOPGEN]) == tg, bar);
;             __builtin_amdgcn_fence(__ATOMIC_ACQUIRE, "agent");
;             xb_add(&bar[XB_XGEN(b.x)], 1u);
;             asm volatile("s_waitcnt vmcnt(0)" ::: "memory");
;         } else {
;             XB_SPIN(xb_ld(&bar[XB_XGEN(b.x)]) == gen, bar);
.LBB0_853:
	s_and_b32 s3, s2, 0xff
	s_mov_b64 s[18:19], -1
	s_cmp_lg_u32 s3, 0
	s_mov_b64 s[22:23], -1
	s_cbranch_scc0 .LBB0_856
	s_and_b64 vcc, exec, s[22:23]
	s_cbranch_vccz .LBB0_852

; __device__ __forceinline__ unsigned xb_ld(unsigned* p)              { return __hip_atomic_load(p, __ATOMIC_RELAXED, __HIP_MEMORY_SCOPE_AGENT); }
; #define XB_SPIN(cond, bar) do { unsigned _sp = 0; while (cond) { __builtin_amdgcn_s_sleep(1); \
;     if ((++_sp & 255u) == 0u) { if (xb_ld(&(bar)[XB_TMO])) break; if (_sp > XB_SPIN_CAP) { atomicAdd(&(bar)[XB_TMO], 1u); break; } } } } while (0)
; __device__ __forceinline__ void xcd_barrier(const XcdBarrier& b) {
;     ...
;             else XB_SPIN(xb_ld(&bar[XB_TOPGEN]) == tg, bar);
.LBB0_870:
	s_and_b32 s3, s2, 0xff
	s_mov_b64 s[16:17], -1
	s_cmp_lg_u32 s3, 0
	s_mov_b64 s[20:21], -1
	s_cbranch_scc0 .LBB0_873
	s_and_b64 vcc, exec, s[20:21]
	s_cbranch_vccz .LBB0_869
